# hand-written RW scan producer too (token x 4-channel threads, dwordx2 loads, b128 LDS writes) + consumer
# speedup vs baseline: 1.0358x; 1.0155x over previous
; DN void rw_scan_item(const Params& p, int l, int item, bool need_ctx, int mode) {
;     ...
;   __syncthreads();
;   if (half == 1) {
;     const int ch = tid & 63, c256 = hh * 64 + ch;
;     ...
;     const int rq = tid >> 4, j16 = tid & 15;
;     f32x2 S[4][2];
; #pragma unroll
;     for (int k = 0; k < 4; ++k) { S[k][0] = (f32x2){0.f, 0.f}; S[k][1] = (f32x2){0.f, 0.f}; }
.LBB0_511:
	v_readfirstlane_b32 s2, v182
	s_lshr_b32 s2, s2, 8
	s_barrier
	s_cmp_lg_u32 s2, 0
	s_cbranch_scc1 .Lrw_prod
	v_and_b32_e32 v149, 1, v183
	v_and_b32_e32 v150, 2, v183
	v_cmp_ne_u32_e64 s[6:7], 0, v149
	v_cmp_ne_u32_e64 s[8:9], 0, v150
	v_lshlrev_b32_e32 v150, 1, v150
	v_lshl_add_u32 v151, v149, 1, v150
	v_bfe_u32 v149, v183, 2, 1
	v_add_u32_e32 v151, v151, v149
	v_lshrrev_b32_e32 v150, 3, v183
	v_lshlrev_b32_e32 v150, 3, v150
	v_lshl_add_u32 v151, v151, 8, v150
	v_and_b32_e32 v149, 7, v183
	v_lshlrev_b32_e32 v149, 5, v149
	v_mov_b32_e32 v0, 0
	v_mov_b32_e32 v1, 0
	v_mov_b32_e32 v2, 0
	v_mov_b32_e32 v3, 0
	v_mov_b32_e32 v4, 0
	v_mov_b32_e32 v5, 0
	v_mov_b32_e32 v6, 0
	v_mov_b32_e32 v7, 0
	v_mov_b32_e32 v8, 0
	v_mov_b32_e32 v9, 0
	v_mov_b32_e32 v10, 0
	v_mov_b32_e32 v11, 0
	v_mov_b32_e32 v12, 0
	v_mov_b32_e32 v13, 0
	v_mov_b32_e32 v14, 0
	v_mov_b32_e32 v15, 0
	s_mov_b32 s2, 0
	s_barrier

; DI int oidx(int i) { asm volatile("" : "+s"(i)); return i; }
; DI float bf2f(bfr u) { return __uint_as_float(((unsigned)u) << 16); }
; DN void rw_scan_item(const Params& p, int l, int item, bool need_ctx, int mode) {
;     ...
;     const int ch = tid & 63, c256 = hh * 64 + ch;
;     const float* mu = p.in[oidx(10)] + (size_t)l * 2 * 1152;
;     const float mr0 = mu[c256], mr1 = mu[1152 + c256], mk0 = mu[256 + c256], mk1 = mu[1152 + 256 + c256], mv0 = mu[512 + c256], mv1 = mu[1152 + 512 + c256];
;     const float kkw = p.in[oidx(16)][l * 256 + c256], kaw = p.in[oidx(17)][l * 256 + c256];
;     auto gload = [&](RwRegs& R, int c) {
; #pragma unroll
;       for (int i = 0; i < 4; ++i) {
;         int s = (tid >> 6) + 4 * i;
;         int t = tokof(c * 16 + s);
;         size_t m = (size_t)b * TT + t;
;         bool hp = (t != 0 && t != TL), hn = (t != TL - 1 && t != TT - 1);
;         const bfr* row = P + m * PW + c256;
;         R.lr[i][1] = row[0]; R.lk[i][1] = row[256]; R.lv[i][1] = row[512];
;         R.lr[i][0] = hp ? row[-PW] : (bfr)0; R.lk[i][0] = hp ? row[256 - PW] : (bfr)0; R.lv[i][0] = hp ? row[512 - PW] : (bfr)0;
;         R.lr[i][2] = hn ? row[PW] : (bfr)0; R.lk[i][2] = hn ? row[256 + PW] : (bfr)0; R.lv[i][2] = hn ? row[512 + PW] : (bfr)0;
;         R.le[i] = RWE[m * 256 + c256]; R.la[i] = RWA[m * 256 + c256];
;       }
;     };
;     auto prep = [&](const RwRegs& R, int c) {
;       float* vec = lbase + (c & 1) * 7168;
;       float* vvv = vec + 16 * 5 * 64;
; #pragma unroll
;       for (int i = 0; i < 4; ++i) {
;         int s = (tid >> 6) + 4 * i;
;         float r0 = bf2f(R.lr[i][1]), k0 = bf2f(R.lk[i][1]), v0 = bf2f(R.lv[i][1]);
;         float rr = r0 + mr0 * (bf2f(R.lr[i][0]) - r0) + mr1 * (bf2f(R.lr[i][2]) - r0);
;         float kx = k0 + mk0 * (bf2f(R.lk[i][0]) - k0) + mk1 * (bf2f(R.lk[i][2]) - k0);
;         float vx = v0 + mv0 * (bf2f(R.lv[i][0]) - v0) + mv1 * (bf2f(R.lv[i][2]) - v0);
.Lrw_prod:
	s_and_b32 s13, s38, 1
	s_bfe_u32 s14, s38, 0x20001
	s_lshr_b32 s15, s38, 3
	v_readlane_b32 s16, v253, 13
	s_load_dwordx2 s[2:3], s[0:1], 0x108
	s_load_dwordx2 s[18:19], s[0:1], 0x50
	s_load_dwordx2 s[20:21], s[0:1], 0x80
	s_load_dwordx2 s[22:23], s[0:1], 0x88
	v_and_b32_e32 v33, 15, v183
	v_lshrrev_b32_e32 v32, 4, v183
	v_lshlrev_b32_e32 v35, 4, v33
	v_mul_u32_u24_e32 v34, 0x500, v32
	v_add_u32_e32 v34, v34, v35
	v_lshl_add_u32 v35, v32, 8, v35
	v_lshlrev_b32_e32 v62, 4, v33
	v_lshlrev_b32_e32 v33, 3, v33
	s_lshl_b32 s24, s13, 1
	s_sub_i32 s24, 1, s24
	v_mul_lo_u32 v32, v32, s24
	s_movk_i32 s34, 0x800
	s_lshl_b32 s25, s14, 7
	s_waitcnt lgkmcnt(0)
	s_mul_i32 s26, s15, 0xe58000
	s_add_u32 s4, s2, 0x737c100
	s_addc_u32 s5, s3, 0
	s_add_u32 s4, s4, s26
	s_addc_u32 s5, s5, 0
	s_add_u32 s4, s4, s25
	s_addc_u32 s5, s5, 0
	s_mul_i32 s26, s15, 0x120000
	s_mul_i32 s27, s13, 0x1200000
	s_add_u32 s26, s26, s27
	s_add_u32 s26, s26, s25
	s_add_u32 s6, s2, 0x158fc100
	s_addc_u32 s7, s3, 0
	s_add_u32 s6, s6, s26
	s_addc_u32 s7, s7, 0
	s_add_u32 s8, s6, 0x2400000
	s_addc_u32 s9, s7, 0
	s_add_u32 s10, s2, 0x1b2fc100
	s_addc_u32 s11, s3, 0
	s_add_u32 s10, s10, s26
	s_addc_u32 s11, s11, 0
	s_mul_i32 s27, s16, 0x2400
	s_lshl_b32 s28, s14, 8
	s_add_u32 s27, s27, s28
	s_add_u32 s18, s18, s27
	s_addc_u32 s19, s19, 0
	s_add_u32 s30, s18, 0x1200
	s_addc_u32 s31, s19, 0
	s_lshl_b32 s27, s16, 10
	s_add_u32 s27, s27, s28
	s_add_u32 s20, s20, s27
	s_addc_u32 s21, s21, 0
	s_add_u32 s22, s22, s27
	s_addc_u32 s23, s23, 0
	global_load_dwordx4 v[0:3], v62, s[18:19]
	global_load_dwordx4 v[4:7], v62, s[30:31]
	global_load_dwordx4 v[8:11], v62, s[18:19] offset:1024
	global_load_dwordx4 v[12:15], v62, s[30:31] offset:1024
	global_load_dwordx4 v[16:19], v62, s[18:19] offset:2048
	global_load_dwordx4 v[20:23], v62, s[30:31] offset:2048
	global_load_dwordx4 v[24:27], v62, s[20:21]
	global_load_dwordx4 v[28:31], v62, s[22:23]
	s_movk_i32 s16, 0x1980
	s_mov_b32 s35, 0
	s_lshl_b32 s30, s35, 4
	s_cmp_lt_u32 s35, 16
	s_cselect_b32 s31, s34, 0xffffff00
	s_add_i32 s31, s30, s31
	s_sub_i32 s30, 0x8ff, s30
	s_cmp_eq_u32 s13, 0
	s_cselect_b32 s17, s31, s30
	v_add_u32_e32 v62, s17, v32
	v_and_b32_e32 v63, 0xfffff7ff, v62
	v_cmp_ne_u32_e64 s[20:21], 0, v63
	v_add_u32_e32 v63, 1, v62
	v_and_b32_e32 v63, 0xfffffeff, v63
	v_cmp_ne_u32_e64 s[22:23], s34, v63
	v_mad_u32_u24 v58, v62, s16, v33
	v_lshl_add_u32 v61, v62, 9, v33
	v_subrev_u32_e32 v59, s16, v58
	v_add_u32_e32 v60, s16, v58
	v_cndmask_b32_e64 v59, v58, v59, s[20:21]
	v_cndmask_b32_e64 v60, v58, v60, s[22:23]
	global_load_dwordx2 v[36:37], v58, s[4:5]
	global_load_dwordx2 v[38:39], v58, s[4:5] offset:512
	global_load_dwordx2 v[40:41], v58, s[4:5] offset:1024
	global_load_dwordx2 v[42:43], v59, s[4:5]
	global_load_dwordx2 v[44:45], v59, s[4:5] offset:512
	global_load_dwordx2 v[46:47], v59, s[4:5] offset:1024
	global_load_dwordx2 v[48:49], v60, s[4:5]
	global_load_dwordx2 v[50:51], v60, s[4:5] offset:512
	global_load_dwordx2 v[52:53], v60, s[4:5] offset:1024
	global_load_dwordx2 v[54:55], v61, s[6:7]
	global_load_dwordx2 v[56:57], v61, s[8:9]
	s_mov_b32 s12, -1
.Lrwp_iter:
	s_waitcnt vmcnt(0)
	s_add_i32 s35, s12, 1
	s_cmpk_gt_i32 s35, 0x8f
	s_cbranch_scc1 .Lrwp_noprep
	s_mov_b64 s[24:25], s[20:21]
	s_mov_b64 s[26:27], s[22:23]
	s_bitcmp1_b32 s35, 0
	s_cselect_b32 s36, 0x7000, 0
	v_cndmask_b32_e64 v42, 0, v42, s[24:25]
	v_cndmask_b32_e64 v43, 0, v43, s[24:25]
	v_cndmask_b32_e64 v44, 0, v44, s[24:25]
	v_cndmask_b32_e64 v45, 0, v45, s[24:25]
	v_cndmask_b32_e64 v46, 0, v46, s[24:25]
	v_cndmask_b32_e64 v47, 0, v47, s[24:25]
	v_cndmask_b32_e64 v48, 0, v48, s[26:27]
	v_cndmask_b32_e64 v49, 0, v49, s[26:27]
	v_cndmask_b32_e64 v50, 0, v50, s[26:27]
	v_cndmask_b32_e64 v51, 0, v51, s[26:27]
	v_cndmask_b32_e64 v52, 0, v52, s[26:27]
	v_cndmask_b32_e64 v53, 0, v53, s[26:27]
	v_lshlrev_b32_e32 v80, 16, v36
	v_and_b32_e32 v81, 0xffff0000, v36
	v_lshlrev_b32_e32 v82, 16, v37
	v_and_b32_e32 v83, 0xffff0000, v37
	v_lshlrev_b32_e32 v92, 16, v42
	v_and_b32_e32 v93, 0xffff0000, v42
	v_lshlrev_b32_e32 v94, 16, v43
	v_and_b32_e32 v95, 0xffff0000, v43
	v_lshlrev_b32_e32 v96, 16, v48
	v_and_b32_e32 v97, 0xffff0000, v48
	v_lshlrev_b32_e32 v98, 16, v49
	v_and_b32_e32 v99, 0xffff0000, v49
	v_sub_f32_e32 v92, v92, v80
	v_sub_f32_e32 v93, v93, v81
	v_sub_f32_e32 v94, v94, v82
	v_sub_f32_e32 v95, v95, v83
	v_sub_f32_e32 v96, v96, v80
	v_sub_f32_e32 v97, v97, v81
	v_sub_f32_e32 v98, v98, v82
	v_sub_f32_e32 v99, v99, v83
	v_fmac_f32_e32 v80, v0, v92
	v_fmac_f32_e32 v81, v1, v93
	v_fmac_f32_e32 v82, v2, v94
	v_fmac_f32_e32 v83, v3, v95
	v_fmac_f32_e32 v80, v4, v96
	v_fmac_f32_e32 v81, v5, v97
	v_fmac_f32_e32 v82, v6, v98
	v_fmac_f32_e32 v83, v7, v99
	v_lshlrev_b32_e32 v100, 16, v38
	v_and_b32_e32 v101, 0xffff0000, v38
	v_lshlrev_b32_e32 v102, 16, v39
	v_and_b32_e32 v103, 0xffff0000, v39
	v_lshlrev_b32_e32 v92, 16, v44
	v_and_b32_e32 v93, 0xffff0000, v44
	v_lshlrev_b32_e32 v94, 16, v45
	v_and_b32_e32 v95, 0xffff0000, v45
	v_lshlrev_b32_e32 v96, 16, v50
	v_and_b32_e32 v97, 0xffff0000, v50
	v_lshlrev_b32_e32 v98, 16, v51
	v_and_b32_e32 v99, 0xffff0000, v51
	v_sub_f32_e32 v92, v92, v100
	v_sub_f32_e32 v93, v93, v101
	v_sub_f32_e32 v94, v94, v102
	v_sub_f32_e32 v95, v95, v103
	v_sub_f32_e32 v96, v96, v100
	v_sub_f32_e32 v97, v97, v101
	v_sub_f32_e32 v98, v98, v102
	v_sub_f32_e32 v99, v99, v103
	v_fmac_f32_e32 v100, v8, v92
	v_fmac_f32_e32 v101, v9, v93
	v_fmac_f32_e32 v102, v10, v94
	v_fmac_f32_e32 v103, v11, v95
	v_fmac_f32_e32 v100, v12, v96
	v_fmac_f32_e32 v101, v13, v97
	v_fmac_f32_e32 v102, v14, v98
	v_fmac_f32_e32 v103, v15, v99
; DI bfr f2bf(float x) { unsigned u = __float_as_uint(x); u += 0x7fffu + ((u >> 16) & 1u); return (bfr)(u >> 16); }
; DI float bf2f(bfr u) { return __uint_as_float(((unsigned)u) << 16); }
; DN void rw_scan_item(const Params& p, int l, int item, bool need_ctx, int mode) {
;     ...
;         float r0 = bf2f(R.lr[i][1]), k0 = bf2f(R.lk[i][1]), v0 = bf2f(R.lv[i][1]);
;         float rr = r0 + mr0 * (bf2f(R.lr[i][0]) - r0) + mr1 * (bf2f(R.lr[i][2]) - r0);
;         float kx = k0 + mk0 * (bf2f(R.lk[i][0]) - k0) + mk1 * (bf2f(R.lk[i][2]) - k0);
;         float vx = v0 + mv0 * (bf2f(R.lv[i][0]) - v0) + mv1 * (bf2f(R.lv[i][2]) - v0);
;         float kkp = kx * kkw;
;         float ss = wave_sum(kkp * kkp);
;         float kk = kkp * rsqrtf(ss + 1e-12f);
;         float a = bf2f(R.la[i]);
;         float wdec = __expf(-bf2f(R.le[i]));
;         float kd = kx * (1.f + (a - 1.f) * kaw);
;         float* vs = vec + s * 320;
;         vs[ch] = wdec; vs[64 + ch] = kd; vs[128 + ch] = -kk; vs[192 + ch] = kk * a; vs[256 + ch] = rr;
;         vvv[s * 64 + ch] = vx;
;       }
;     };
;     auto yout = [&](int cprev) {
;       const float* yb = lbase + (cprev & 1) * 7168 + 16 * 5 * 64 + 16 * 64;
; #pragma unroll
;       for (int i = 0; i < 4; ++i) {
;         int idx = tid + 256 * i;
;         int s = idx >> 6, rr = idx & 63;
;         int t = tokof(cprev * 16 + s);
;         if (t < TL || need_ctx) Y[((size_t)b * TT + t) * 256 + hh * 64 + rr] = f2bf(yb[s * 64 + rr]);
;       }
;     };
;     RwRegs RA, RB;
;     gload(RA, 0);
;     gload(RB, 1);
;     prep(RA, 0);
;     if (mode != 2) gload(RA, 2);
;     __syncthreads();
; #pragma unroll 1
;     for (int c = 0; c < nchunks; c += 2) {
;       prep(RB, c + 1);
;       if (c + 3 < nchunks && mode != 2) gload(RB, c + 3);
;       if (c > 0 && mode == 0) yout(c - 1);
;       __syncthreads();
;       if (c + 2 < nchunks) prep(RA, c + 2);
;       if (c + 4 < nchunks && mode != 2) gload(RA, c + 4);
;       if (mode == 0) yout(c);
;       __syncthreads();
;     }
;     if (mode == 0) yout(nchunks - 1);
	v_lshlrev_b32_e32 v84, 16, v40
	v_and_b32_e32 v85, 0xffff0000, v40
	v_lshlrev_b32_e32 v86, 16, v41
	v_and_b32_e32 v87, 0xffff0000, v41
	v_lshlrev_b32_e32 v92, 16, v46
	v_and_b32_e32 v93, 0xffff0000, v46
	v_lshlrev_b32_e32 v94, 16, v47
	v_and_b32_e32 v95, 0xffff0000, v47
	v_lshlrev_b32_e32 v96, 16, v52
	v_and_b32_e32 v97, 0xffff0000, v52
	v_lshlrev_b32_e32 v98, 16, v53
	v_and_b32_e32 v99, 0xffff0000, v53
	v_sub_f32_e32 v92, v92, v84
	v_sub_f32_e32 v93, v93, v85
	v_sub_f32_e32 v94, v94, v86
	v_sub_f32_e32 v95, v95, v87
	v_sub_f32_e32 v96, v96, v84
	v_sub_f32_e32 v97, v97, v85
	v_sub_f32_e32 v98, v98, v86
	v_sub_f32_e32 v99, v99, v87
	v_fmac_f32_e32 v84, v16, v92
	v_fmac_f32_e32 v85, v17, v93
	v_fmac_f32_e32 v86, v18, v94
	v_fmac_f32_e32 v87, v19, v95
	v_fmac_f32_e32 v84, v20, v96
	v_fmac_f32_e32 v85, v21, v97
	v_fmac_f32_e32 v86, v22, v98
	v_fmac_f32_e32 v87, v23, v99
	v_mul_f32_e32 v104, v100, v24
	v_mul_f32_e32 v105, v101, v25
	v_mul_f32_e32 v106, v102, v26
	v_mul_f32_e32 v107, v103, v27
	v_mul_f32_e32 v108, v104, v104
	v_fmac_f32_e32 v108, v105, v105
	v_fmac_f32_e32 v108, v106, v106
	v_fmac_f32_e32 v108, v107, v107
	v_lshlrev_b32_e32 v112, 16, v56
	v_and_b32_e32 v113, 0xffff0000, v56
	v_add_f32_dpp v108, v108, v108 quad_perm:[1,0,3,2] row_mask:0xf bank_mask:0xf bound_ctrl:1
	v_lshlrev_b32_e32 v114, 16, v57
	v_and_b32_e32 v115, 0xffff0000, v57
	v_add_f32_dpp v108, v108, v108 quad_perm:[2,3,0,1] row_mask:0xf bank_mask:0xf bound_ctrl:1
	v_lshlrev_b32_e32 v64, 16, v54
	v_and_b32_e32 v65, 0xffff0000, v54
	v_add_f32_dpp v108, v108, v108 row_half_mirror row_mask:0xf bank_mask:0xf bound_ctrl:1
	v_lshlrev_b32_e32 v66, 16, v55
	v_and_b32_e32 v67, 0xffff0000, v55
	v_add_f32_dpp v108, v108, v108 row_mirror row_mask:0xf bank_mask:0xf bound_ctrl:1
	v_add_f32_e32 v108, 0x2b8cbccc, v108
	v_rsq_f32_e32 v108, v108
	v_mul_f32_e32 v64, 0xbfb8aa3b, v64
	v_mul_f32_e32 v65, 0xbfb8aa3b, v65
	v_mul_f32_e32 v66, 0xbfb8aa3b, v66
	v_mul_f32_e32 v67, 0xbfb8aa3b, v67
	v_exp_f32_e32 v64, v64
	v_exp_f32_e32 v65, v65
	v_exp_f32_e32 v66, v66
	v_exp_f32_e32 v67, v67
	v_add_f32_e32 v116, -1.0, v112
	v_add_f32_e32 v117, -1.0, v113
	v_add_f32_e32 v118, -1.0, v114
	v_add_f32_e32 v119, -1.0, v115
	v_fma_f32 v116, v28, v116, 1.0
	v_fma_f32 v117, v29, v117, 1.0
	v_fma_f32 v118, v30, v118, 1.0
	v_fma_f32 v119, v31, v119, 1.0
	v_mul_f32_e32 v68, v100, v116
	v_mul_f32_e32 v69, v101, v117
	v_mul_f32_e32 v70, v102, v118
	v_mul_f32_e32 v71, v103, v119
	v_mul_f32_e64 v72, v104, -v108
	v_mul_f32_e64 v73, v105, -v108
	v_mul_f32_e64 v74, v106, -v108
	v_mul_f32_e64 v75, v107, -v108
	v_mul_f32_e64 v76, -v72, v112
	v_mul_f32_e64 v77, -v73, v113
	v_mul_f32_e64 v78, -v74, v114
	v_mul_f32_e64 v79, -v75, v115
	v_add_u32_e32 v62, s36, v34
	v_add_u32_e32 v63, s36, v35
	ds_write_b128 v62, v[64:67]
	ds_write_b128 v62, v[68:71] offset:256
	ds_write_b128 v62, v[72:75] offset:512
	ds_write_b128 v62, v[76:79] offset:768
	ds_write_b128 v62, v[80:83] offset:1024
	ds_write_b128 v63, v[84:87] offset:20480
.Lrwp_noprep:
	s_add_i32 s35, s12, 2
	s_cmpk_gt_i32 s35, 0x8f
	s_cbranch_scc1 .Lrwp_noload
	s_lshl_b32 s30, s35, 4
	s_cmp_lt_u32 s35, 16
	s_cselect_b32 s31, s34, 0xffffff00
	s_add_i32 s31, s30, s31
	s_sub_i32 s30, 0x8ff, s30
	s_cmp_eq_u32 s13, 0
	s_cselect_b32 s17, s31, s30
	v_add_u32_e32 v62, s17, v32
	v_and_b32_e32 v63, 0xfffff7ff, v62
	v_cmp_ne_u32_e64 s[20:21], 0, v63
	v_add_u32_e32 v63, 1, v62
	v_and_b32_e32 v63, 0xfffffeff, v63
	v_cmp_ne_u32_e64 s[22:23], s34, v63
	v_mad_u32_u24 v58, v62, s16, v33
	v_lshl_add_u32 v61, v62, 9, v33
	v_subrev_u32_e32 v59, s16, v58
	v_add_u32_e32 v60, s16, v58
	v_cndmask_b32_e64 v59, v58, v59, s[20:21]
	v_cndmask_b32_e64 v60, v58, v60, s[22:23]
	global_load_dwordx2 v[36:37], v58, s[4:5]
	global_load_dwordx2 v[38:39], v58, s[4:5] offset:512
	global_load_dwordx2 v[40:41], v58, s[4:5] offset:1024
	global_load_dwordx2 v[42:43], v59, s[4:5]
	global_load_dwordx2 v[44:45], v59, s[4:5] offset:512
	global_load_dwordx2 v[46:47], v59, s[4:5] offset:1024
	global_load_dwordx2 v[48:49], v60, s[4:5]
	global_load_dwordx2 v[50:51], v60, s[4:5] offset:512
	global_load_dwordx2 v[52:53], v60, s[4:5] offset:1024
	global_load_dwordx2 v[54:55], v61, s[6:7]
	global_load_dwordx2 v[56:57], v61, s[8:9]
.Lrwp_noload:
	s_cmp_lt_i32 s12, 1
	s_cbranch_scc1 .Lrwp_noy
	s_add_i32 s35, s12, -1
	s_cmp_lg_u64 s[92:93], 0
	s_cbranch_scc1 .Lrwp_doy
	s_cmp_lt_i32 s35, 16
	s_cbranch_scc1 .Lrwp_noy
.Lrwp_doy:
	s_lshl_b32 s30, s35, 4
	s_cmp_lt_u32 s35, 16
	s_cselect_b32 s31, s34, 0xffffff00
	s_add_i32 s31, s30, s31
	s_sub_i32 s30, 0x8ff, s30
	s_cmp_eq_u32 s13, 0
	s_cselect_b32 s17, s31, s30
	s_bitcmp1_b32 s35, 0
	s_cselect_b32 s36, 0x7000, 0
	v_add_u32_e32 v62, s36, v35
	ds_read_b128 v[88:91], v62 offset:24576
	v_add_u32_e32 v63, s17, v32
	v_lshl_add_u32 v63, v63, 9, v33
	s_waitcnt lgkmcnt(0)
	v_cvt_pk_bf16_f32 v88, v88, v89
	v_cvt_pk_bf16_f32 v89, v90, v91
	global_store_dwordx2 v63, v[88:89], s[10:11]
.Lrwp_noy:
	s_add_i32 s12, s12, 1
	s_cmpk_lt_i32 s12, 0x90
	s_waitcnt lgkmcnt(0)
	s_barrier
	s_cbranch_scc1 .Lrwp_iter
	s_movk_i32 s35, 0x8f
	s_lshl_b32 s30, s35, 4
	s_cmp_lt_u32 s35, 16
	s_cselect_b32 s31, s34, 0xffffff00
	s_add_i32 s31, s30, s31
	s_sub_i32 s30, 0x8ff, s30
	s_cmp_eq_u32 s13, 0
	s_cselect_b32 s17, s31, s30
	s_bitcmp1_b32 s35, 0
	s_cselect_b32 s36, 0x7000, 0
	v_add_u32_e32 v62, s36, v35
	ds_read_b128 v[88:91], v62 offset:24576
	v_add_u32_e32 v63, s17, v32
	v_lshl_add_u32 v63, v63, 9, v33
	s_waitcnt lgkmcnt(0)
	v_cvt_pk_bf16_f32 v88, v88, v89
	v_cvt_pk_bf16_f32 v89, v90, v91
	global_store_dwordx2 v63, v[88:89], s[10:11]
	s_branch .LBB0_510
